# diff unit boundary restructure + fox two-tile software-pipelined fast path
# speedup vs baseline: 1.0178x; 1.0019x over previous
; #define LAS __attribute__((address_space(3)))
; template <int MODE, int NDG> ...
;     ...
;     LAS const unsigned char* kp = kst + r32 * 144 + hi * 16;
;     {   f32x16 z;
; #pragma unroll
;         for (int r = 0; r < 16; ++r) z[r] = 0.f;
;         const bf16x8 a0 = lds16(kp), a1 = lds16(kp + 32 * 144);
;         p0 = __builtin_amdgcn_mfma_f32_32x32x16_bf16(a0, qr[0], MODE == MODE_SB ? z : negm, 0, 0, 0);
;         p1 = __builtin_amdgcn_mfma_f32_32x32x16_bf16(a1, qr[0], MODE == MODE_SB ? z : negm, 0, 0, 0); }
; #pragma unroll
;     for (int d0 = 1; d0 < 4; ++d0) {
;         const bf16x8 a0 = lds16(kp + d0 * 32), a1 = lds16(kp + 32 * 144 + d0 * 32);
;         p0 = __builtin_amdgcn_mfma_f32_32x32x16_bf16(a0, qr[d0], p0, 0, 0, 0);
;         p1 = __builtin_amdgcn_mfma_f32_32x32x16_bf16(a1, qr[d0], p1, 0, 0, 0);
;     }
;     ...
;     if (MODE == MODE_DIFF) { f32x16 d0_ = p0, d1_ = p1;
; #pragma unroll
;         for (int d0 = 0; d0 < 4; ++d0) { d0_ = __builtin_amdgcn_mfma_f32_32x32x16_bf16(qr[d0], qr[d0], d0_, 0, 0, 0); d1_ = __builtin_amdgcn_mfma_f32_32x32x16_bf16(qr[d0], qr[d0], d1_, 0, 0, 0); }
;         asm volatile("" :: "v"(d0_), "v"(d1_)); }
;     ...
;     if (MODE == MODE_DIFF) {
; #pragma unroll
;         for (int d0 = 0; d0 < 4; ++d0) { const bf16x8 a0 = lds16(kp + d0 * 32 + 64 * 144), a1 = lds16(kp + 32 * 144 + d0 * 32 + 64 * 144); asm volatile("" :: "v"(a0), "v"(a1)); }
;         LAS const unsigned char* vq = vst + ((lane >> 4) & 1) * 32 + (lane & 3) * 8 + (4 * hi + ((lane & 15) >> 2)) * 64;
; #pragma unroll
;         for (int i = 0; i < 8; ++i) { const bf16x8 vf = vfrag(vq + i * 1024); asm volatile("" :: "v"(vf)); } }
;     ...
;     if (MODE == MODE_FOX) {
;         const bf16x8 a0 = lds16(ast + r32 * 16), a1 = lds16(ast + (32 + r32) * 16);
;         const short one = hi ? (short)0 : (short)0x3F80;
;         const bf16x8 qa = (bf16x8){one, one, one, 0, 0, 0, 0, 0};
;         p0 = __builtin_amdgcn_mfma_f32_32x32x16_bf16(a0, qa, p0, 0, 0, 0);
;         p1 = __builtin_amdgcn_mfma_f32_32x32x16_bf16(a1, qa, p1, 0, 0, 0);
;     }
;     ...
;         float a = fmaxf(fmaxf(p0[0], p0[1]), p1[0]), b = fmaxf(fmaxf(p0[2], p0[3]), p1[1]); a = fmaxf(fmaxf(a, p1[2]), p1[3]);
; #pragma unroll
;         for (int r = 4; r < 16; r += 4) { a = fmaxf(fmaxf(a, p0[r]), p0[r + 1]); b = fmaxf(fmaxf(b, p0[r + 2]), p0[r + 3]); a = fmaxf(fmaxf(a, p1[r]), p1[r + 1]); b = fmaxf(fmaxf(b, p1[r + 2]), p1[r + 3]); }
.Lfx_try:
	s_add_i32 s3, s36, s42
	s_addk_i32 s3, 0xff
	s_cmp_lt_i32 s3, s37
	s_cbranch_scc0 .LBB0_234
	s_cmp_eq_u32 s46, 0x41000000
	s_cbranch_scc0 .LBB0_234
	v_add3_u32 v194, s24, v172, v137
	v_add3_u32 v194, v194, v173, v174
	ds_read_b128 v[4:7], v185 offset:9216
	ds_read_b128 v[8:11], v185 offset:13824
	ds_read_b128 v[12:15], v185 offset:9248
	ds_read_b128 v[234:237], v185 offset:13856
	ds_read_b128 v[238:241], v185 offset:9280
	ds_read_b128 v[242:245], v185 offset:13888
	s_waitcnt lgkmcnt(5)
	v_mfma_f32_32x32x16_bf16 v[80:95], v[4:7], v[100:103], v[48:63]
	ds_read_b128 v[4:7], v185 offset:9312
	s_waitcnt lgkmcnt(5)
	v_mfma_f32_32x32x16_bf16 v[64:79], v[8:11], v[100:103], v[48:63]
	ds_read_b128 v[8:11], v185 offset:13920
	s_waitcnt lgkmcnt(5)
	v_mfma_f32_32x32x16_bf16 v[80:95], v[12:15], v[104:107], v[80:95]
	ds_read_b128 v[12:15], v3 offset:35840
	s_waitcnt lgkmcnt(5)
	v_mfma_f32_32x32x16_bf16 v[64:79], v[234:237], v[104:107], v[64:79]
	ds_read_b128 v[234:237], v3 offset:36352
	s_waitcnt lgkmcnt(5)
	v_mfma_f32_32x32x16_bf16 v[80:95], v[238:241], v[108:111], v[80:95]
	ds_read_b128 v[238:241], v185
	s_waitcnt lgkmcnt(5)
	v_mfma_f32_32x32x16_bf16 v[64:79], v[242:245], v[108:111], v[64:79]
	ds_read_b128 v[242:245], v185 offset:4608
	s_waitcnt lgkmcnt(5)
	v_mfma_f32_32x32x16_bf16 v[80:95], v[4:7], v[112:115], v[80:95]
	ds_read_b128 v[4:7], v185 offset:32
	s_waitcnt lgkmcnt(5)
	v_mfma_f32_32x32x16_bf16 v[64:79], v[8:11], v[112:115], v[64:79]
	ds_read_b128 v[8:11], v185 offset:4640
	s_waitcnt lgkmcnt(5)
	v_mfma_f32_32x32x16_bf16 v[80:95], v[12:15], v[96:99], v[80:95]
	ds_read_b128 v[12:15], v185 offset:64
	s_waitcnt lgkmcnt(5)
	v_mfma_f32_32x32x16_bf16 v[64:79], v[234:237], v[96:99], v[64:79]
	ds_read_b128 v[234:237], v185 offset:4672
	s_waitcnt lgkmcnt(5)
	v_mfma_f32_32x32x16_bf16 v[202:217], v[238:241], v[100:103], v[48:63]
	ds_read_b128 v[238:241], v185 offset:96
	s_waitcnt lgkmcnt(5)
	v_mfma_f32_32x32x16_bf16 v[218:233], v[242:245], v[100:103], v[48:63]
	ds_read_b128 v[242:245], v185 offset:4704
	s_waitcnt lgkmcnt(5)
	v_mfma_f32_32x32x16_bf16 v[202:217], v[4:7], v[104:107], v[202:217]
	ds_read_b128 v[4:7], v3 offset:34816
	s_waitcnt lgkmcnt(5)
	v_mfma_f32_32x32x16_bf16 v[218:233], v[8:11], v[104:107], v[218:233]
	ds_read_b128 v[8:11], v3 offset:35328
	s_waitcnt lgkmcnt(5)
	v_mfma_f32_32x32x16_bf16 v[202:217], v[12:15], v[108:111], v[202:217]
	v_max3_f32 v0, v80, v81, v82
	v_max3_f32 v1, v83, v84, v85
	v_max3_f32 v0, v0, v86, v87
	v_max3_f32 v1, v1, v88, v89
	v_max3_f32 v0, v0, v90, v91
	v_max3_f32 v1, v1, v92, v93
	v_max3_f32 v0, v0, v94, v95
	s_waitcnt lgkmcnt(4)
	v_mfma_f32_32x32x16_bf16 v[218:233], v[234:237], v[108:111], v[218:233]
	v_max3_f32 v1, v1, v64, v65
	v_max3_f32 v0, v0, v66, v67
	v_max3_f32 v1, v1, v68, v69
	v_max3_f32 v0, v0, v70, v71
	v_max3_f32 v1, v1, v72, v73
	v_max3_f32 v0, v0, v74, v75
	v_max3_f32 v1, v1, v76, v77
	s_waitcnt lgkmcnt(3)
	v_mfma_f32_32x32x16_bf16 v[202:217], v[238:241], v[112:115], v[202:217]
	v_max3_f32 v0, v0, v78, v79
	v_max_f32_e32 v0, v0, v1
	v_mov_b32_e32 v1, v0
	v_mov_b32_e32 v198, v0
	s_nop 1
	v_permlane32_swap_b32_e32 v1, v198
	v_xor_b32_e32 v1, v1, v198
	s_waitcnt lgkmcnt(2)
	v_mfma_f32_32x32x16_bf16 v[218:233], v[242:245], v[112:115], v[218:233]
	v_xor_b32_e32 v1, v1, v0
	v_max_f32_e32 v1, v1, v1
	v_max_f32_e32 v0, v0, v1
	s_waitcnt lgkmcnt(1)
	v_mfma_f32_32x32x16_bf16 v[202:217], v[4:7], v[96:99], v[202:217]
	s_waitcnt lgkmcnt(0)
	v_mfma_f32_32x32x16_bf16 v[218:233], v[8:11], v[96:99], v[218:233]
	v_cmp_lt_f32_e32 vcc, s46, v0
	s_cbranch_vccnz .LBB0_234
	ds_read_b64_tr_b16 v[4:5], v194 offset:26624
	ds_read_b64_tr_b16 v[6:7], v194 offset:27136
	ds_read_b64_tr_b16 v[8:9], v194 offset:30720
	ds_read_b64_tr_b16 v[10:11], v194 offset:31232
	ds_read_b64_tr_b16 v[12:13], v194 offset:27648
	ds_read_b64_tr_b16 v[14:15], v194 offset:28160
	ds_read_b64_tr_b16 v[234:235], v194 offset:31744
	ds_read_b64_tr_b16 v[236:237], v194 offset:32256
	ds_read_b64_tr_b16 v[238:239], v194 offset:28672
	ds_read_b64_tr_b16 v[240:241], v194 offset:29184
	ds_read_b64_tr_b16 v[242:243], v194 offset:32768
	ds_read_b64_tr_b16 v[244:245], v194 offset:33280
	s_nop 3
	v_max3_f32 v1, v202, v203, v204
	v_max3_f32 v199, v205, v206, v207
	v_max3_f32 v1, v1, v208, v209
	v_max3_f32 v199, v199, v210, v211
	v_max3_f32 v1, v1, v212, v213
	v_max3_f32 v199, v199, v214, v215
	v_max3_f32 v1, v1, v216, v217
	v_max3_f32 v199, v199, v218, v219
	v_max3_f32 v1, v1, v220, v221
	v_max3_f32 v199, v199, v222, v223
	v_max3_f32 v1, v1, v224, v225
	v_max3_f32 v199, v199, v226, v227
	v_max3_f32 v1, v1, v228, v229
	v_max3_f32 v199, v199, v230, v231
	v_max3_f32 v1, v1, v232, v233
	v_max_f32_e32 v1, v1, v199
	v_mov_b32_e32 v199, v1
	v_mov_b32_e32 v198, v1
	s_nop 1
	v_permlane32_swap_b32_e32 v199, v198
	v_xor_b32_e32 v199, v199, v198
	v_xor_b32_e32 v199, v199, v1
	v_max_f32_e32 v199, v199, v199
	v_max_f32_e32 v1, v1, v199
	v_cmp_lt_f32_e32 vcc, s46, v1
	s_cbranch_vccnz .LBB0_234
; __device__ __forceinline__ unsigned cvtpk(float lo, float hi) { f32x2 v = {lo, hi}; bf16x2_t b = __builtin_convertvector(v, bf16x2_t); return __builtin_bit_cast(unsigned, b); }
; #define LAS __attribute__((address_space(3)))
; template <int MODE, int NDG> ...
;     ...
;         float s0 = 0.f, s1 = 0.f;
; #pragma unroll
;         for (int r = 0; r < 16; ++r) { p0[r] = __builtin_amdgcn_exp2f(p0[r]); p1[r] = __builtin_amdgcn_exp2f(p1[r]); s0 += p0[r]; s1 += p1[r]; }
;         l += s0 + s1;
;         pw[0] = (u32x4){cvtpk(p0[0], p0[1]), cvtpk(p0[2], p0[3]), cvtpk(p0[4], p0[5]), cvtpk(p0[6], p0[7])};
;         pw[1] = (u32x4){cvtpk(p0[8], p0[9]), cvtpk(p0[10], p0[11]), cvtpk(p0[12], p0[13]), cvtpk(p0[14], p0[15])};
;         pw[2] = (u32x4){cvtpk(p1[0], p1[1]), cvtpk(p1[2], p1[3]), cvtpk(p1[4], p1[5]), cvtpk(p1[6], p1[7])};
;         pw[3] = (u32x4){cvtpk(p1[8], p1[9]), cvtpk(p1[10], p1[11]), cvtpk(p1[12], p1[13]), cvtpk(p1[14], p1[15])};
;     }
;     LAS const unsigned char* vp = vst + ((lane >> 4) & 1) * 32 + (lane & 3) * 8 + (4 * hi + ((lane & 15) >> 2)) * 64;
; #pragma unroll
;     for (int ks = 0; ks < 4; ++ks)
; #pragma unroll
;         for (int dg = 0; dg < NDG; ++dg) {
;             const bf16x8 vf = vfrag(vp + dg * 4096 + ks * 1024);
;             o[dg] = __builtin_amdgcn_mfma_f32_32x32x16_bf16(vf, __builtin_bit_cast(bf16x8, pw[ks]), o[dg], 0, 0, 0);
;         }
	v_exp_f32_e32 v80, v80
	v_exp_f32_e32 v81, v81
	v_exp_f32_e32 v82, v82
	v_exp_f32_e32 v83, v83
	v_exp_f32_e32 v84, v84
	v_exp_f32_e32 v85, v85
	v_exp_f32_e32 v86, v86
	v_exp_f32_e32 v87, v87
	v_mov_b32_e32 v0, v80
	v_mov_b32_e32 v1, v81
	v_add_f32_e32 v0, v0, v82
	v_add_f32_e32 v1, v1, v83
	v_add_f32_e32 v0, v0, v84
	v_add_f32_e32 v1, v1, v85
	v_add_f32_e32 v0, v0, v86
	v_add_f32_e32 v1, v1, v87
	v_cvt_pk_bf16_f32 v80, v80, v81
	v_cvt_pk_bf16_f32 v81, v82, v83
	v_cvt_pk_bf16_f32 v82, v84, v85
	v_cvt_pk_bf16_f32 v83, v86, v87
	s_nop 1
	s_waitcnt lgkmcnt(10)
	v_mfma_f32_32x32x16_bf16 v[32:47], v[4:7], v[80:83], v[32:47]
	ds_read_b64_tr_b16 v[186:187], v194 offset:29696
	ds_read_b64_tr_b16 v[188:189], v194 offset:30208
	v_exp_f32_e32 v88, v88
	v_exp_f32_e32 v89, v89
	v_exp_f32_e32 v90, v90
	v_exp_f32_e32 v91, v91
	v_exp_f32_e32 v92, v92
	v_exp_f32_e32 v93, v93
	v_exp_f32_e32 v94, v94
	s_waitcnt lgkmcnt(10)
	v_mfma_f32_32x32x16_bf16 v[16:31], v[8:11], v[80:83], v[16:31]
	ds_read_b64_tr_b16 v[190:191], v194 offset:33792
	ds_read_b64_tr_b16 v[192:193], v194 offset:34304
	v_exp_f32_e32 v95, v95
	v_add_f32_e32 v0, v0, v88
	v_add_f32_e32 v1, v1, v89
	v_add_f32_e32 v0, v0, v90
	v_add_f32_e32 v1, v1, v91
	v_add_f32_e32 v0, v0, v92
	v_add_f32_e32 v1, v1, v93
	v_add_f32_e32 v0, v0, v94
	v_add_f32_e32 v1, v1, v95
	v_cvt_pk_bf16_f32 v88, v88, v89
	v_cvt_pk_bf16_f32 v89, v90, v91
	v_cvt_pk_bf16_f32 v90, v92, v93
	v_cvt_pk_bf16_f32 v91, v94, v95
	s_nop 1
	s_waitcnt lgkmcnt(10)
	v_mfma_f32_32x32x16_bf16 v[32:47], v[12:15], v[88:91], v[32:47]
	ds_read_b64_tr_b16 v[4:5], v194 offset:18432
	ds_read_b64_tr_b16 v[6:7], v194 offset:18944
	v_exp_f32_e32 v64, v64
	v_exp_f32_e32 v65, v65
	v_exp_f32_e32 v66, v66
	v_exp_f32_e32 v67, v67
	v_exp_f32_e32 v68, v68
	v_exp_f32_e32 v69, v69
	v_exp_f32_e32 v70, v70
	s_waitcnt lgkmcnt(10)
	v_mfma_f32_32x32x16_bf16 v[16:31], v[234:237], v[88:91], v[16:31]
	ds_read_b64_tr_b16 v[8:9], v194 offset:22528
	ds_read_b64_tr_b16 v[10:11], v194 offset:23040
	v_exp_f32_e32 v71, v71
	v_add_f32_e32 v0, v0, v64
	v_add_f32_e32 v1, v1, v65
	v_add_f32_e32 v0, v0, v66
	v_add_f32_e32 v1, v1, v67
	v_add_f32_e32 v0, v0, v68
	v_add_f32_e32 v1, v1, v69
	v_add_f32_e32 v0, v0, v70
	v_add_f32_e32 v1, v1, v71
	v_cvt_pk_bf16_f32 v64, v64, v65
	v_cvt_pk_bf16_f32 v65, v66, v67
	v_cvt_pk_bf16_f32 v66, v68, v69
	v_cvt_pk_bf16_f32 v67, v70, v71
	s_nop 1
	s_waitcnt lgkmcnt(10)
	v_mfma_f32_32x32x16_bf16 v[32:47], v[238:241], v[64:67], v[32:47]
	ds_read_b64_tr_b16 v[12:13], v194 offset:19456
	ds_read_b64_tr_b16 v[14:15], v194 offset:19968
	v_exp_f32_e32 v72, v72
	v_exp_f32_e32 v73, v73
	v_exp_f32_e32 v74, v74
	v_exp_f32_e32 v75, v75
	v_exp_f32_e32 v76, v76
	v_exp_f32_e32 v77, v77
	v_exp_f32_e32 v78, v78
	s_waitcnt lgkmcnt(10)
	v_mfma_f32_32x32x16_bf16 v[16:31], v[242:245], v[64:67], v[16:31]
	ds_read_b64_tr_b16 v[234:235], v194 offset:23552
	ds_read_b64_tr_b16 v[236:237], v194 offset:24064
	v_exp_f32_e32 v79, v79
	v_add_f32_e32 v0, v0, v72
	v_add_f32_e32 v1, v1, v73
	v_add_f32_e32 v0, v0, v74
	v_add_f32_e32 v1, v1, v75
	v_add_f32_e32 v0, v0, v76
	v_add_f32_e32 v1, v1, v77
	v_add_f32_e32 v0, v0, v78
	v_add_f32_e32 v1, v1, v79
	v_cvt_pk_bf16_f32 v72, v72, v73
	v_cvt_pk_bf16_f32 v73, v74, v75
	v_cvt_pk_bf16_f32 v74, v76, v77
	v_cvt_pk_bf16_f32 v75, v78, v79
	s_nop 1
	s_waitcnt lgkmcnt(10)
	v_mfma_f32_32x32x16_bf16 v[32:47], v[186:189], v[72:75], v[32:47]
	ds_read_b64_tr_b16 v[238:239], v194 offset:20480
	ds_read_b64_tr_b16 v[240:241], v194 offset:20992
	v_exp_f32_e32 v202, v202
	v_exp_f32_e32 v203, v203
	v_exp_f32_e32 v204, v204
	v_exp_f32_e32 v205, v205
	v_exp_f32_e32 v206, v206
	v_exp_f32_e32 v207, v207
	v_exp_f32_e32 v208, v208
	s_waitcnt lgkmcnt(10)
	v_mfma_f32_32x32x16_bf16 v[16:31], v[190:193], v[72:75], v[16:31]
	ds_read_b64_tr_b16 v[242:243], v194 offset:24576
	ds_read_b64_tr_b16 v[244:245], v194 offset:25088
	v_exp_f32_e32 v209, v209
	v_add_f32_e32 v0, v0, v202
	v_add_f32_e32 v1, v1, v203
	v_add_f32_e32 v0, v0, v204
	v_add_f32_e32 v1, v1, v205
	v_add_f32_e32 v0, v0, v206
	v_add_f32_e32 v1, v1, v207
	v_add_f32_e32 v0, v0, v208
	v_add_f32_e32 v1, v1, v209
	v_cvt_pk_bf16_f32 v202, v202, v203
	v_cvt_pk_bf16_f32 v203, v204, v205
	v_cvt_pk_bf16_f32 v204, v206, v207
	v_cvt_pk_bf16_f32 v205, v208, v209
	s_nop 1
	s_waitcnt lgkmcnt(10)
	v_mfma_f32_32x32x16_bf16 v[32:47], v[4:7], v[202:205], v[32:47]
	ds_read_b64_tr_b16 v[186:187], v194 offset:21504
	ds_read_b64_tr_b16 v[188:189], v194 offset:22016
	v_exp_f32_e32 v210, v210
	v_exp_f32_e32 v211, v211
	v_exp_f32_e32 v212, v212
	v_exp_f32_e32 v213, v213
	v_exp_f32_e32 v214, v214
	v_exp_f32_e32 v215, v215
	v_exp_f32_e32 v216, v216
	s_waitcnt lgkmcnt(10)
	v_mfma_f32_32x32x16_bf16 v[16:31], v[8:11], v[202:205], v[16:31]
	ds_read_b64_tr_b16 v[190:191], v194 offset:25600
	ds_read_b64_tr_b16 v[192:193], v194 offset:26112
	v_exp_f32_e32 v217, v217
	v_add_f32_e32 v0, v0, v210
	v_add_f32_e32 v1, v1, v211
	v_add_f32_e32 v0, v0, v212
	v_add_f32_e32 v1, v1, v213
	v_add_f32_e32 v0, v0, v214
	v_add_f32_e32 v1, v1, v215
	v_add_f32_e32 v0, v0, v216
	v_add_f32_e32 v1, v1, v217
	v_cvt_pk_bf16_f32 v210, v210, v211
	v_cvt_pk_bf16_f32 v211, v212, v213
	v_cvt_pk_bf16_f32 v212, v214, v215
	v_cvt_pk_bf16_f32 v213, v216, v217
	s_nop 1
	s_waitcnt lgkmcnt(10)
	v_mfma_f32_32x32x16_bf16 v[32:47], v[12:15], v[210:213], v[32:47]
	v_exp_f32_e32 v218, v218
	v_exp_f32_e32 v219, v219
	v_exp_f32_e32 v220, v220
	v_exp_f32_e32 v221, v221
	v_exp_f32_e32 v222, v222
	v_exp_f32_e32 v223, v223
	v_exp_f32_e32 v224, v224
	s_waitcnt lgkmcnt(8)
	v_mfma_f32_32x32x16_bf16 v[16:31], v[234:237], v[210:213], v[16:31]
	v_exp_f32_e32 v225, v225
	v_add_f32_e32 v0, v0, v218
	v_add_f32_e32 v1, v1, v219
	v_add_f32_e32 v0, v0, v220
	v_add_f32_e32 v1, v1, v221
	v_add_f32_e32 v0, v0, v222
	v_add_f32_e32 v1, v1, v223
	v_add_f32_e32 v0, v0, v224
	v_add_f32_e32 v1, v1, v225
	v_cvt_pk_bf16_f32 v218, v218, v219
	v_cvt_pk_bf16_f32 v219, v220, v221
	v_cvt_pk_bf16_f32 v220, v222, v223
	v_cvt_pk_bf16_f32 v221, v224, v225
	s_nop 1
	s_waitcnt lgkmcnt(6)
	v_mfma_f32_32x32x16_bf16 v[32:47], v[238:241], v[218:221], v[32:47]
	v_exp_f32_e32 v226, v226
	v_exp_f32_e32 v227, v227
	v_exp_f32_e32 v228, v228
	v_exp_f32_e32 v229, v229
	v_exp_f32_e32 v230, v230
	v_exp_f32_e32 v231, v231
	v_exp_f32_e32 v232, v232
	s_waitcnt lgkmcnt(4)
	v_mfma_f32_32x32x16_bf16 v[16:31], v[242:245], v[218:221], v[16:31]
	v_exp_f32_e32 v233, v233
	v_add_f32_e32 v0, v0, v226
	v_add_f32_e32 v1, v1, v227
	v_add_f32_e32 v0, v0, v228
	v_add_f32_e32 v1, v1, v229
	v_add_f32_e32 v0, v0, v230
	v_add_f32_e32 v1, v1, v231
	v_add_f32_e32 v0, v0, v232
	v_add_f32_e32 v1, v1, v233
	v_cvt_pk_bf16_f32 v226, v226, v227
	v_cvt_pk_bf16_f32 v227, v228, v229
	v_cvt_pk_bf16_f32 v228, v230, v231
	v_cvt_pk_bf16_f32 v229, v232, v233
	s_nop 1
	s_waitcnt lgkmcnt(2)
	v_mfma_f32_32x32x16_bf16 v[32:47], v[186:189], v[226:229], v[32:47]
	v_add_f32_e32 v0, v0, v1
	v_add_f32_e32 v184, v184, v0
	s_waitcnt lgkmcnt(0)
	v_mfma_f32_32x32x16_bf16 v[16:31], v[190:193], v[226:229], v[16:31]
	s_branch .LBB0_233
